# phase 1 big tiles: epilogue transposes through LDS and stores full 128B rows (dwordx4)
# speedup vs baseline: 1.0305x; 1.0305x over previous
.LBB0_116:
	s_or_b64 exec, exec, s[0:1]
	s_add_u32 s0, s94, 0x15000000
	s_addc_u32 s1, s95, 0
	s_add_u32 s28, s94, 0x6c00000
	v_writelane_b32 v242, s0, 50
	s_addc_u32 s29, s95, 0
	v_mov_b32_e32 v0, v199
	v_writelane_b32 v242, s1, 51
	s_add_u32 s0, s94, 0xd000000
	s_addc_u32 s1, s95, 0
	v_writelane_b32 v242, s0, 52
	s_barrier
	s_nop 0
	v_writelane_b32 v242, s1, 53
	s_nop 0
	v_readlane_b32 s0, v242, 45
	v_readlane_b32 s1, v242, 46
	s_cmpk_gt_i32 s0, 0x29ff
	v_writelane_b32 v242, s58, 54
	s_nop 1
	v_writelane_b32 v242, s59, 55
	s_cbranch_scc1 .LBB0_246
	s_mov_b32 s91, 0
	s_cmp_lg_u32 s96, 0x200
	s_cbranch_scc1 .Lbig_skip
	v_lshrrev_b32_e32 v236, 3, v199
	v_lshrrev_b32_e32 v237, 4, v199
	v_xor_b32_e32 v237, v237, v199
	v_and_b32_e32 v237, 7, v237
	v_lshlrev_b32_e32 v237, 4, v237
	v_lshl_add_u32 v192, v236, 12, v237
	v_add_u32_e32 v193, 0x20000, v192
	v_add_u32_e32 v194, 0x40000, v192
	v_add_u32_e32 v195, 0x60000, v192
	v_and_b32_e32 v236, 15, v199
	v_bfe_u32 v237, v199, 4, 2
	v_lshrrev_b32_e32 v238, 1, v236
	v_lshlrev_b32_e32 v202, 3, v237
	v_xor_b32_e32 v237, v237, v238
	v_lshlrev_b32_e32 v237, 4, v237
	v_xor_b32_e32 v238, 64, v237
	v_lshrrev_b32_e32 v201, 7, v199
	v_lshl_add_u32 v201, v201, 7, v236
	v_lshlrev_b32_e32 v196, 7, v201
	v_bfe_u32 v198, v199, 6, 1
	v_lshl_add_u32 v202, v198, 7, v202
	v_lshl_add_u32 v198, v198, 6, v236
	v_lshlrev_b32_e32 v198, 7, v198
	v_add_u32_e32 v198, 0x8000, v198
	v_add_u32_e32 v197, v196, v238
	v_add_u32_e32 v200, v198, v238
	v_add_u32_e32 v196, v196, v237
	v_add_u32_e32 v198, v198, v237
	v_lshrrev_b32_e32 v236, 6, v199
	v_lshlrev_b32_e32 v236, 10, v236
	s_nop 0
	v_readfirstlane_b32 s32, v236
	v_lshrrev_b32_e32 v240, 6, v199
	v_mul_u32_u24_e32 v240, 0x900, v240
	v_add_u32_e32 v240, 0xc000, v240
	v_and_b32_e32 v241, 15, v199
	v_mul_u32_u24_e32 v241, 0x90, v241
	v_bfe_u32 v238, v199, 4, 2
	v_lshl_add_u32 v241, v238, 3, v241
	v_add_u32_e32 v236, v240, v241
	v_and_b32_e32 v241, 63, v199
	v_lshrrev_b32_e32 v238, 3, v241
	v_mul_u32_u24_e32 v238, 0x90, v238
	v_and_b32_e32 v241, 7, v241
	v_lshl_add_u32 v238, v241, 4, v238
	v_add_u32_e32 v237, v240, v238
	v_readlane_b32 s90, v242, 45
	s_and_b32 s51, s90, 63
	s_lshl_b32 s51, s51, 20
	s_add_u32 s36, s94, s51
	s_addc_u32 s37, s95, 0
	s_add_u32 s36, s36, 0x15000000
	s_addc_u32 s37, s37, 0
	s_lshr_b32 s51, s90, 6
	s_lshl_b32 s51, s51, 19
	s_add_u32 s44, s94, s51
	s_addc_u32 s45, s95, 0
	s_add_u32 s44, s44, 0x19000000
	s_addc_u32 s45, s45, 0
	s_add_u32 s40, s36, 0x80000
	s_addc_u32 s41, s37, 0
	s_and_b32 s21, s90, 31
	s_mov_b32 s20, s21
	s_lshl_b32 s51, s21, 7
	s_add_u32 s36, s36, s51
	s_addc_u32 s37, s37, 0
	s_add_u32 s40, s40, s51
	s_addc_u32 s41, s41, 0
	s_add_u32 s44, s44, s51
	s_addc_u32 s45, s45, 0
	s_barrier
	s_add_u32 m0, s32, 0x0
	s_nop 0
	global_load_lds_dwordx4 v192, s[36:37]
	s_add_u32 m0, s32, 0x1000
	s_nop 0
	global_load_lds_dwordx4 v193, s[36:37]
	s_add_u32 m0, s32, 0x2000
	s_nop 0
	global_load_lds_dwordx4 v194, s[36:37]
	s_add_u32 m0, s32, 0x3000
	s_nop 0
	global_load_lds_dwordx4 v195, s[36:37]
	s_add_u32 m0, s32, 0x4000
	s_nop 0
	global_load_lds_dwordx4 v192, s[40:41]
	s_add_u32 m0, s32, 0x5000
	s_nop 0
	global_load_lds_dwordx4 v193, s[40:41]
	s_add_u32 m0, s32, 0x6000
	s_nop 0
	global_load_lds_dwordx4 v194, s[40:41]
	s_add_u32 m0, s32, 0x7000
	s_nop 0
	global_load_lds_dwordx4 v195, s[40:41]
	s_add_u32 m0, s32, 0x8000
	s_nop 0
	global_load_lds_dwordx4 v192, s[44:45]
	s_add_u32 m0, s32, 0x9000
	s_nop 0
	global_load_lds_dwordx4 v193, s[44:45]
	s_add_u32 m0, s32, 0xa000
	s_nop 0
	global_load_lds_dwordx4 v194, s[44:45]
	s_add_u32 m0, s32, 0xb000
	s_nop 0
	global_load_lds_dwordx4 v195, s[44:45]
	s_add_u32 s36, s36, 0x80
	s_addc_u32 s37, s37, 0
	s_add_u32 s40, s40, 0x80
	s_addc_u32 s41, s41, 0
	s_add_u32 s44, s44, 0x80
	s_addc_u32 s45, s45, 0
	s_add_i32 s20, s20, 1
	s_cmp_eq_u32 s20, 32
	s_cbranch_scc1 .Lbig_wrap0

.Lbig_tile:
	s_add_u32 s91, s90, 0x200
	s_and_b32 s51, s91, 63
	s_lshl_b32 s51, s51, 20
	s_add_u32 s46, s94, s51
	s_addc_u32 s47, s95, 0
	s_add_u32 s46, s46, 0x15000000
	s_addc_u32 s47, s47, 0
	s_lshr_b32 s51, s91, 6
	s_lshl_b32 s51, s51, 19
	s_add_u32 s48, s94, s51
	s_addc_u32 s49, s95, 0
	s_add_u32 s48, s48, 0x19000000
	s_addc_u32 s49, s49, 0
	s_lshl_b32 s51, s21, 7
	s_add_u32 s46, s46, s51
	s_addc_u32 s47, s47, 0
	s_add_u32 s48, s48, s51
	s_addc_u32 s49, s49, 0
	v_mov_b32_e32 v0, 0
	v_mov_b32_e32 v1, 0
	v_mov_b32_e32 v2, 0
	v_mov_b32_e32 v3, 0
	v_mov_b32_e32 v4, 0
	v_mov_b32_e32 v5, 0
	v_mov_b32_e32 v6, 0
	v_mov_b32_e32 v7, 0
	v_mov_b32_e32 v8, 0
	v_mov_b32_e32 v9, 0
	v_mov_b32_e32 v10, 0
	v_mov_b32_e32 v11, 0
	v_mov_b32_e32 v12, 0
	v_mov_b32_e32 v13, 0
	v_mov_b32_e32 v14, 0
	v_mov_b32_e32 v15, 0
	v_mov_b32_e32 v16, 0
	v_mov_b32_e32 v17, 0
	v_mov_b32_e32 v18, 0
	v_mov_b32_e32 v19, 0
	v_mov_b32_e32 v20, 0
	v_mov_b32_e32 v21, 0
	v_mov_b32_e32 v22, 0
	v_mov_b32_e32 v23, 0
	v_mov_b32_e32 v24, 0
	v_mov_b32_e32 v25, 0
	v_mov_b32_e32 v26, 0
	v_mov_b32_e32 v27, 0
	v_mov_b32_e32 v28, 0
	v_mov_b32_e32 v29, 0
	v_mov_b32_e32 v30, 0
	v_mov_b32_e32 v31, 0
	v_mov_b32_e32 v32, 0
	v_mov_b32_e32 v33, 0
	v_mov_b32_e32 v34, 0
	v_mov_b32_e32 v35, 0
	v_mov_b32_e32 v36, 0
	v_mov_b32_e32 v37, 0
	v_mov_b32_e32 v38, 0
	v_mov_b32_e32 v39, 0
	v_mov_b32_e32 v40, 0
	v_mov_b32_e32 v41, 0
	v_mov_b32_e32 v42, 0
	v_mov_b32_e32 v43, 0
	v_mov_b32_e32 v44, 0
	v_mov_b32_e32 v45, 0
	v_mov_b32_e32 v46, 0
	v_mov_b32_e32 v47, 0
	v_mov_b32_e32 v48, 0
	v_mov_b32_e32 v49, 0
	v_mov_b32_e32 v50, 0
	v_mov_b32_e32 v51, 0
	v_mov_b32_e32 v52, 0
	v_mov_b32_e32 v53, 0
	v_mov_b32_e32 v54, 0
	v_mov_b32_e32 v55, 0
	v_mov_b32_e32 v56, 0
	v_mov_b32_e32 v57, 0
	v_mov_b32_e32 v58, 0
	v_mov_b32_e32 v59, 0
	v_mov_b32_e32 v60, 0
	v_mov_b32_e32 v61, 0
	v_mov_b32_e32 v62, 0
	v_mov_b32_e32 v63, 0
	v_mov_b32_e32 v64, 0
	v_mov_b32_e32 v65, 0
	v_mov_b32_e32 v66, 0
	v_mov_b32_e32 v67, 0
	v_mov_b32_e32 v68, 0
	v_mov_b32_e32 v69, 0
	v_mov_b32_e32 v70, 0
	v_mov_b32_e32 v71, 0
	v_mov_b32_e32 v72, 0
	v_mov_b32_e32 v73, 0
	v_mov_b32_e32 v74, 0
	v_mov_b32_e32 v75, 0
	v_mov_b32_e32 v76, 0
	v_mov_b32_e32 v77, 0
	v_mov_b32_e32 v78, 0
	v_mov_b32_e32 v79, 0
	v_mov_b32_e32 v80, 0
	v_mov_b32_e32 v81, 0
	v_mov_b32_e32 v82, 0
	v_mov_b32_e32 v83, 0
	v_mov_b32_e32 v84, 0
	v_mov_b32_e32 v85, 0
	v_mov_b32_e32 v86, 0
	v_mov_b32_e32 v87, 0
	v_mov_b32_e32 v88, 0
	v_mov_b32_e32 v89, 0
	v_mov_b32_e32 v90, 0
	v_mov_b32_e32 v91, 0
	v_mov_b32_e32 v92, 0
	v_mov_b32_e32 v93, 0
	v_mov_b32_e32 v94, 0
	v_mov_b32_e32 v95, 0
	v_mov_b32_e32 v96, 0
	v_mov_b32_e32 v97, 0
	v_mov_b32_e32 v98, 0
	v_mov_b32_e32 v99, 0
	v_mov_b32_e32 v100, 0
	v_mov_b32_e32 v101, 0
	v_mov_b32_e32 v102, 0
	v_mov_b32_e32 v103, 0
	v_mov_b32_e32 v104, 0
	v_mov_b32_e32 v105, 0
	v_mov_b32_e32 v106, 0
	v_mov_b32_e32 v107, 0
	v_mov_b32_e32 v108, 0
	v_mov_b32_e32 v109, 0
	v_mov_b32_e32 v110, 0
	v_mov_b32_e32 v111, 0
	v_mov_b32_e32 v112, 0
	v_mov_b32_e32 v113, 0
	v_mov_b32_e32 v114, 0
	v_mov_b32_e32 v115, 0
	v_mov_b32_e32 v116, 0
	v_mov_b32_e32 v117, 0
	v_mov_b32_e32 v118, 0
	v_mov_b32_e32 v119, 0
	v_mov_b32_e32 v120, 0
	v_mov_b32_e32 v121, 0
	v_mov_b32_e32 v122, 0
	v_mov_b32_e32 v123, 0
	v_mov_b32_e32 v124, 0
	v_mov_b32_e32 v125, 0
	v_mov_b32_e32 v126, 0
	v_mov_b32_e32 v127, 0
	s_mov_b32 s50, 0
	s_waitcnt vmcnt(16)
	s_branch .Lbig_k_in

.Lbig_reg:
	s_sub_u32 s51, s51, s19
	s_lshl_b32 s51, s51, 1
	s_mul_i32 s17, s17, s16
	s_add_u32 s17, s17, s51
	s_add_u32 s17, s17, s18
	s_add_u32 s14, s94, s17
	s_addc_u32 s15, s95, 0
	s_lshl_b32 s16, s16, 4
	v_and_b32_e32 v241, 63, v199
	v_lshrrev_b32_e32 v240, 3, v241
	v_lshrrev_b32_e32 v238, 7, v199
	v_lshl_add_u32 v238, v238, 7, v240
	v_mul_lo_u32 v203, v238, s16
	v_lshrrev_b32_e32 v203, 4, v203
	v_and_b32_e32 v240, 7, v241
	v_lshl_add_u32 v203, v240, 4, v203
	v_bfe_u32 v240, v199, 6, 1
	v_lshl_add_u32 v203, v240, 7, v203
	s_lshr_b32 s17, s16, 1
	v_add_u32_e32 v238, s17, v203
	v_cvt_pk_bf16_f32 v128, v0, v1
	v_cvt_pk_bf16_f32 v129, v2, v3
	ds_write_b64 v236, v[128:129] offset:0
	v_cvt_pk_bf16_f32 v130, v4, v5
	v_cvt_pk_bf16_f32 v131, v6, v7
	ds_write_b64 v236, v[130:131] offset:32
	v_cvt_pk_bf16_f32 v128, v8, v9
	v_cvt_pk_bf16_f32 v129, v10, v11
	ds_write_b64 v236, v[128:129] offset:64
	v_cvt_pk_bf16_f32 v130, v12, v13
	v_cvt_pk_bf16_f32 v131, v14, v15
	ds_write_b64 v236, v[130:131] offset:96
	s_waitcnt lgkmcnt(0)
	ds_read_b128 v[136:139], v237
	ds_read_b128 v[140:143], v237 offset:1152
	s_waitcnt lgkmcnt(0)
	global_store_dwordx4 v203, v[136:139], s[14:15]
	global_store_dwordx4 v238, v[140:143], s[14:15]
	s_add_u32 s14, s14, s16
	s_addc_u32 s15, s15, 0
	v_cvt_pk_bf16_f32 v128, v16, v17
	v_cvt_pk_bf16_f32 v129, v18, v19
	ds_write_b64 v236, v[128:129] offset:0
	v_cvt_pk_bf16_f32 v130, v20, v21
	v_cvt_pk_bf16_f32 v131, v22, v23
	ds_write_b64 v236, v[130:131] offset:32
	v_cvt_pk_bf16_f32 v128, v24, v25
	v_cvt_pk_bf16_f32 v129, v26, v27
	ds_write_b64 v236, v[128:129] offset:64
	v_cvt_pk_bf16_f32 v130, v28, v29
	v_cvt_pk_bf16_f32 v131, v30, v31
	ds_write_b64 v236, v[130:131] offset:96
	s_waitcnt lgkmcnt(0)
	ds_read_b128 v[136:139], v237
	ds_read_b128 v[140:143], v237 offset:1152
	s_waitcnt lgkmcnt(0)
	global_store_dwordx4 v203, v[136:139], s[14:15]
	global_store_dwordx4 v238, v[140:143], s[14:15]
	s_add_u32 s14, s14, s16
	s_addc_u32 s15, s15, 0
	v_cvt_pk_bf16_f32 v128, v32, v33
	v_cvt_pk_bf16_f32 v129, v34, v35
	ds_write_b64 v236, v[128:129] offset:0
	v_cvt_pk_bf16_f32 v130, v36, v37
	v_cvt_pk_bf16_f32 v131, v38, v39
	ds_write_b64 v236, v[130:131] offset:32
	v_cvt_pk_bf16_f32 v128, v40, v41
	v_cvt_pk_bf16_f32 v129, v42, v43
	ds_write_b64 v236, v[128:129] offset:64
	v_cvt_pk_bf16_f32 v130, v44, v45
	v_cvt_pk_bf16_f32 v131, v46, v47
	ds_write_b64 v236, v[130:131] offset:96
	s_waitcnt lgkmcnt(0)
	ds_read_b128 v[136:139], v237
	ds_read_b128 v[140:143], v237 offset:1152
	s_waitcnt lgkmcnt(0)
	global_store_dwordx4 v203, v[136:139], s[14:15]
	global_store_dwordx4 v238, v[140:143], s[14:15]
	s_add_u32 s14, s14, s16
	s_addc_u32 s15, s15, 0
	v_cvt_pk_bf16_f32 v128, v48, v49
	v_cvt_pk_bf16_f32 v129, v50, v51
	ds_write_b64 v236, v[128:129] offset:0
	v_cvt_pk_bf16_f32 v130, v52, v53
	v_cvt_pk_bf16_f32 v131, v54, v55
	ds_write_b64 v236, v[130:131] offset:32
	v_cvt_pk_bf16_f32 v128, v56, v57
	v_cvt_pk_bf16_f32 v129, v58, v59
	ds_write_b64 v236, v[128:129] offset:64
	v_cvt_pk_bf16_f32 v130, v60, v61
	v_cvt_pk_bf16_f32 v131, v62, v63
	ds_write_b64 v236, v[130:131] offset:96
	s_waitcnt lgkmcnt(0)
	ds_read_b128 v[136:139], v237
	ds_read_b128 v[140:143], v237 offset:1152
	s_waitcnt lgkmcnt(0)
	global_store_dwordx4 v203, v[136:139], s[14:15]
	global_store_dwordx4 v238, v[140:143], s[14:15]
	s_add_u32 s14, s14, s16
	s_addc_u32 s15, s15, 0
	v_cvt_pk_bf16_f32 v128, v64, v65
	v_cvt_pk_bf16_f32 v129, v66, v67
	ds_write_b64 v236, v[128:129] offset:0
	v_cvt_pk_bf16_f32 v130, v68, v69
	v_cvt_pk_bf16_f32 v131, v70, v71
	ds_write_b64 v236, v[130:131] offset:32
	v_cvt_pk_bf16_f32 v128, v72, v73
	v_cvt_pk_bf16_f32 v129, v74, v75
	ds_write_b64 v236, v[128:129] offset:64
	v_cvt_pk_bf16_f32 v130, v76, v77
	v_cvt_pk_bf16_f32 v131, v78, v79
	ds_write_b64 v236, v[130:131] offset:96
	s_waitcnt lgkmcnt(0)
	ds_read_b128 v[136:139], v237
	ds_read_b128 v[140:143], v237 offset:1152
	s_waitcnt lgkmcnt(0)
	global_store_dwordx4 v203, v[136:139], s[14:15]
	global_store_dwordx4 v238, v[140:143], s[14:15]
	s_add_u32 s14, s14, s16
	s_addc_u32 s15, s15, 0
	v_cvt_pk_bf16_f32 v128, v80, v81
	v_cvt_pk_bf16_f32 v129, v82, v83
	ds_write_b64 v236, v[128:129] offset:0
	v_cvt_pk_bf16_f32 v130, v84, v85
	v_cvt_pk_bf16_f32 v131, v86, v87
	ds_write_b64 v236, v[130:131] offset:32
	v_cvt_pk_bf16_f32 v128, v88, v89
	v_cvt_pk_bf16_f32 v129, v90, v91
	ds_write_b64 v236, v[128:129] offset:64
	v_cvt_pk_bf16_f32 v130, v92, v93
	v_cvt_pk_bf16_f32 v131, v94, v95
	ds_write_b64 v236, v[130:131] offset:96
	s_waitcnt lgkmcnt(0)
	ds_read_b128 v[136:139], v237
	ds_read_b128 v[140:143], v237 offset:1152
	s_waitcnt lgkmcnt(0)
	global_store_dwordx4 v203, v[136:139], s[14:15]
	global_store_dwordx4 v238, v[140:143], s[14:15]
	s_add_u32 s14, s14, s16
	s_addc_u32 s15, s15, 0
	v_cvt_pk_bf16_f32 v128, v96, v97
	v_cvt_pk_bf16_f32 v129, v98, v99
	ds_write_b64 v236, v[128:129] offset:0
	v_cvt_pk_bf16_f32 v130, v100, v101
	v_cvt_pk_bf16_f32 v131, v102, v103
	ds_write_b64 v236, v[130:131] offset:32
	v_cvt_pk_bf16_f32 v128, v104, v105
	v_cvt_pk_bf16_f32 v129, v106, v107
	ds_write_b64 v236, v[128:129] offset:64
	v_cvt_pk_bf16_f32 v130, v108, v109
	v_cvt_pk_bf16_f32 v131, v110, v111
	ds_write_b64 v236, v[130:131] offset:96
	s_waitcnt lgkmcnt(0)
	ds_read_b128 v[136:139], v237
	ds_read_b128 v[140:143], v237 offset:1152
	s_waitcnt lgkmcnt(0)
	global_store_dwordx4 v203, v[136:139], s[14:15]
	global_store_dwordx4 v238, v[140:143], s[14:15]
	s_add_u32 s14, s14, s16
	s_addc_u32 s15, s15, 0
	v_cvt_pk_bf16_f32 v128, v112, v113
	v_cvt_pk_bf16_f32 v129, v114, v115
	ds_write_b64 v236, v[128:129] offset:0
	v_cvt_pk_bf16_f32 v130, v116, v117
	v_cvt_pk_bf16_f32 v131, v118, v119
	ds_write_b64 v236, v[130:131] offset:32
	v_cvt_pk_bf16_f32 v128, v120, v121
	v_cvt_pk_bf16_f32 v129, v122, v123
	ds_write_b64 v236, v[128:129] offset:64
	v_cvt_pk_bf16_f32 v130, v124, v125
	v_cvt_pk_bf16_f32 v131, v126, v127
	ds_write_b64 v236, v[130:131] offset:96
	s_waitcnt lgkmcnt(0)
	ds_read_b128 v[136:139], v237
	ds_read_b128 v[140:143], v237 offset:1152
	s_waitcnt lgkmcnt(0)
	global_store_dwordx4 v203, v[136:139], s[14:15]
	global_store_dwordx4 v238, v[140:143], s[14:15]
	s_add_u32 s90, s90, 0x200
	s_cmp_lt_u32 s90, 0x1400
	s_cbranch_scc1 .Lbig_tile
	s_waitcnt vmcnt(0)
	s_mov_b32 s91, 1
	s_branch .Lbig_skip
